# combo + GEMM prologues issue K-tile 1 stages before the first wait/barrier (vmcnt(2)->vmcnt(8) after 14 loads)
# speedup vs baseline: 1.0018x; 1.0018x over previous
; #define PG8_STAGE(bufoff, gbase, voff) do { _Pragma("unroll") for (int _i = 0; _i < 2; ++_i) \
;         __builtin_amdgcn_global_load_lds((const unsigned*)((const char*)(gbase) + (voff)[_i]), (PG8_LAS unsigned*)(lds + (bufoff) + ldsw + _i * 8192), 16, 0, 0); } while (0)
; #define PG8_WAIT_V(n) asm volatile("s_waitcnt vmcnt(" #n ")" ::: "memory")
; #define PG8_BAR __builtin_amdgcn_s_barrier()
; template <class Epi, class Sched, bool ALIGN_EPI = false, bool SP2 = false>
; __device__ __forceinline__ void gemm_phase(PG8_LAS unsigned char* lds, const Gemm g, const Sched& S, const Epi& E, volatile PG8_LAS unsigned* sw = nullptr) {
;     ...
;         PG8_STAGE(PG8_SB(0, 0), cB, voffB); PG8_STAGE(PG8_SB(0, 1), cB + hstep, voffB); PG8_STAGE(PG8_SA(0, 0), cA, voffA); PG8_STAGE(PG8_SA(0, 1), cA + hstep, voffA);
;         if (wr == 1) PG8_BAR;
;         PG8_WAIT_V(2); PG8_BAR;
;         PG8_STAGE(PG8_SB(1, 0), cB + kstep, voffB); PG8_STAGE(PG8_SA(1, 0), cA + kstep, voffA); PG8_STAGE(PG8_SB(1, 1), cB + hstep + kstep, voffB);
;         PG8_WAIT_V(6); PG8_BAR;
.LBB0_156:
	s_add_u32 s0, s50, 0x8000
	s_addc_u32 s1, s51, 0
	s_add_u32 s8, s48, 0x8000
	s_addc_u32 s9, s49, 0
	s_add_u32 s10, s50, 0xc000
	s_addc_u32 s11, s51, 0
	s_lshl_b32 s12, s61, 2
	s_add_u32 s33, s91, s12
	s_addc_u32 s40, s92, 0
	s_add_i32 m0, s20, 0x18000
	v_lshl_add_u64 v[10:11], s[0:1], 0, v[134:135]
	global_load_lds_dwordx4 v[10:11], off
	v_lshl_add_u64 v[10:11], s[0:1], 0, v[130:131]
	s_add_i32 m0, s20, 0x1a000
	s_add_i32 s41, s20, 0x8000
	global_load_lds_dwordx4 v[10:11], off
	v_lshl_add_u64 v[10:11], s[8:9], 0, v[136:137]
	s_mov_b32 m0, s41
	s_add_i32 s42, s20, 0xa000
	global_load_lds_dwordx4 v[10:11], off
	v_lshl_add_u64 v[10:11], s[8:9], 0, v[132:133]
	s_mov_b32 m0, s42
	v_and_b32_e32 v9, 15, v2
	global_load_lds_dwordx4 v[10:11], off
	s_add_i32 m0, s20, 0x1c000
	v_lshl_add_u64 v[10:11], s[10:11], 0, v[134:135]
	global_load_lds_dwordx4 v[10:11], off
	v_lshl_add_u64 v[10:11], s[10:11], 0, v[130:131]
	s_add_i32 m0, s20, 0x1e000
	s_and_b32 s0, s3, 3
	global_load_lds_dwordx4 v[10:11], off
	s_waitcnt vmcnt(8)
	s_barrier
	v_bfe_u32 v10, v2, 4, 2
	v_lshlrev_b32_e32 v12, 4, v10
	v_lshlrev_b32_e32 v2, 2, v2
	v_lshl_or_b32 v1, s7, 6, v9
	v_lshl_or_b32 v9, v9, 6, v12
	s_lshl_b32 s1, s7, 13
	v_and_b32_e32 v2, 32, v2
	v_bitop3_b32 v12, v9, s1, v2 bitop3:0xde
	s_lshl_b32 s1, s0, 12
	v_bitop3_b32 v144, v9, s1, v2 bitop3:0xde
	v_lshlrev_b32_e32 v2, 10, v7
	v_and_b32_e32 v2, 0xfffff800, v2
	v_lshl_add_u32 v2, v6, 7, v2
	v_and_b32_e32 v6, 1, v7
	v_lshl_or_b32 v2, v6, 6, v2
	v_lshl_add_u32 v138, v8, 1, v2
	v_lshlrev_b32_e32 v2, 10, v3
	v_and_b32_e32 v2, 0xfffff800, v2
	s_waitcnt vmcnt(6)
	s_cmpk_lt_u32 s6, 0x100
	v_lshl_add_u32 v2, v4, 7, v2
	v_and_b32_e32 v3, 1, v3
	v_lshlrev_b32_e32 v11, 3, v10
	s_cselect_b64 s[6:7], -1, 0
	v_lshl_or_b32 v2, v3, 6, v2
	s_add_i32 s57, 0, 0x10000
	s_add_i32 s58, 0, 0x14000
	s_mov_b32 s43, 0
	v_lshl_or_b32 v145, s0, 5, v11
	v_cmp_eq_u32_e64 s[0:1], 0, v10
	s_bfe_u32 s56, s3, 0x10001
	v_mov_b32_e32 v139, v135
	v_lshl_add_u32 v140, v5, 1, v2
	v_mov_b32_e32 v141, v135
	v_add_u32_e32 v146, s57, v144
	v_add_u32_e32 v147, s58, v144
	v_add_u32_e32 v148, 0, v12
	s_mov_b64 s[8:9], 0x100
	s_barrier
	s_branch .LBB0_159

; #define PG8_STAGE(bufoff, gbase, voff) do { _Pragma("unroll") for (int _i = 0; _i < 2; ++_i) \
;         __builtin_amdgcn_global_load_lds((const unsigned*)((const char*)(gbase) + (voff)[_i]), (PG8_LAS unsigned*)(lds + (bufoff) + ldsw + _i * 8192), 16, 0, 0); } while (0)
; #define PG8_WAIT_V(n) asm volatile("s_waitcnt vmcnt(" #n ")" ::: "memory")
; #define PG8_BAR __builtin_amdgcn_s_barrier()
; template <class Epi, class Sched, bool ALIGN_EPI = false, bool SP2 = false>
; __device__ __forceinline__ void gemm_phase(PG8_LAS unsigned char* lds, const Gemm g, const Sched& S, const Epi& E, volatile PG8_LAS unsigned* sw = nullptr) {
;     ...
;         PG8_STAGE(PG8_SB(0, 0), cB, voffB); PG8_STAGE(PG8_SB(0, 1), cB + hstep, voffB); PG8_STAGE(PG8_SA(0, 0), cA, voffA); PG8_STAGE(PG8_SA(0, 1), cA + hstep, voffA);
;         if (wr == 1) PG8_BAR;
;         PG8_WAIT_V(2); PG8_BAR;
;         PG8_STAGE(PG8_SB(1, 0), cB + kstep, voffB); PG8_STAGE(PG8_SA(1, 0), cA + kstep, voffA); PG8_STAGE(PG8_SB(1, 1), cB + hstep + kstep, voffB);
;         PG8_WAIT_V(6); PG8_BAR;
.LBB0_438:
	s_add_u32 s8, s48, 0x8000
	s_addc_u32 s9, s49, 0
	s_add_u32 s22, s46, 0x8000
	s_addc_u32 s23, s47, 0
	s_add_u32 s24, s48, 0xc000
	s_addc_u32 s25, s49, 0
	s_add_i32 m0, s13, 0x18000
	v_lshl_add_u64 v[10:11], s[8:9], 0, v[150:151]
	global_load_lds_dwordx4 v[10:11], off
	v_lshl_add_u64 v[10:11], s[8:9], 0, v[146:147]
	s_add_i32 m0, s13, 0x1a000
	s_add_i32 s41, s13, 0x8000
	global_load_lds_dwordx4 v[10:11], off
	v_lshl_add_u64 v[10:11], s[22:23], 0, v[152:153]
	s_mov_b32 m0, s41
	s_add_i32 s42, s13, 0xa000
	global_load_lds_dwordx4 v[10:11], off
	v_lshl_add_u64 v[10:11], s[22:23], 0, v[148:149]
	s_mov_b32 m0, s42
	v_bfe_u32 v172, v2, 4, 2
	global_load_lds_dwordx4 v[10:11], off
	s_add_i32 m0, s13, 0x1c000
	v_lshl_add_u64 v[10:11], s[24:25], 0, v[150:151]
	global_load_lds_dwordx4 v[10:11], off
	v_lshl_add_u64 v[10:11], s[24:25], 0, v[146:147]
	s_add_i32 m0, s13, 0x1e000
	v_and_b32_e32 v1, 15, v2
	global_load_lds_dwordx4 v[10:11], off
	s_waitcnt vmcnt(8)
	s_barrier
	v_lshlrev_b32_e32 v9, 4, v172
	v_lshlrev_b32_e32 v2, 2, v2
	s_and_b32 s7, s6, 3
	s_lshl_b32 s43, s5, 6
	v_lshl_or_b32 v9, v1, 6, v9
	s_lshl_b32 s5, s5, 13
	v_and_b32_e32 v2, 32, v2
	v_bitop3_b32 v10, v9, s5, v2 bitop3:0xde
	s_lshl_b32 s5, s7, 12
	v_bitop3_b32 v173, v9, s5, v2 bitop3:0xde
	v_lshlrev_b32_e32 v2, 10, v7
	v_and_b32_e32 v2, 0xfffff800, v2
	v_lshl_add_u32 v2, v6, 7, v2
	v_and_b32_e32 v6, 1, v7
	v_lshl_or_b32 v2, v6, 6, v2
	v_lshl_add_u32 v156, v8, 1, v2
	v_lshlrev_b32_e32 v2, 10, v3
	s_lshl_b32 s54, s7, 5
	v_and_b32_e32 v2, 0xfffff800, v2
	s_waitcnt vmcnt(6)
	s_cmpk_lt_u32 s4, 0x100
	v_lshl_add_u32 v2, v4, 7, v2
	v_and_b32_e32 v3, 1, v3
	s_cselect_b64 s[4:5], -1, 0
	v_lshl_or_b32 v2, v3, 6, v2
	s_add_i32 s57, 0, 0x10000
	s_add_i32 s58, 0, 0x14000
	s_bfe_u32 s55, s6, 0x10001
	s_and_b32 s56, s54, 32
	v_mov_b32_e32 v157, v155
	v_lshl_add_u32 v158, v5, 1, v2
	v_mov_b32_e32 v159, v155
	v_add_u32_e32 v174, s57, v173
	v_add_u32_e32 v175, s58, v173
	v_add_u32_e32 v176, 0, v10
	s_mov_b64 s[6:7], 0xb0200
	s_mov_b32 s59, 0x15000
	s_mov_b32 s30, s10
	s_mov_b32 s65, s12
	s_mov_b32 s64, 0
	s_barrier
	s_branch .LBB0_441

; template <class Epi, class Sched, bool ALIGN_EPI = false, bool SP2 = false>
; __device__ __forceinline__ void gemm_phase(PG8_LAS unsigned char* lds, const Gemm g, const Sched& S, const Epi& E, volatile PG8_LAS unsigned* sw = nullptr) {
;     ...
;         PG8_STAGE(PG8_SB(0, 0), cB, voffB); PG8_STAGE(PG8_SB(0, 1), cB + hstep, voffB); PG8_STAGE(PG8_SA(0, 0), cA, voffA); PG8_STAGE(PG8_SA(0, 1), cA + hstep, voffA);
;         if (wr == 1) PG8_BAR;
;         PG8_WAIT_V(2); PG8_BAR;
;         PG8_STAGE(PG8_SB(1, 0), cB + kstep, voffB); PG8_STAGE(PG8_SA(1, 0), cA + kstep, voffA); PG8_STAGE(PG8_SB(1, 1), cB + hstep + kstep, voffB);
;         PG8_WAIT_V(6); PG8_BAR;
;     __device__ __forceinline__ void run(f32x4 (&acc)[2][2][4][2], const pg8::Unit& u, int wr, int wc, int fr_, int fq_, int buf) const {
;         int fr = fr_, fq = fq_; asm volatile("" : "+v"(fr), "+v"(fq));
;         const int gpm = pm0 + u.pm, colL = wc * 32 + 8 * fq, colg = u.pn * 256 + colL;
;         const LAS float* T = X + 2048 + buf * 1536; const LAS float* TB = T + 512;
;         {   f32x4 rs[2];
; #pragma unroll
;             for (int ai = 0; ai < 2; ++ai) { const f32x4 q = *(const LAS f32x4*)(T + 128 * ai + 64 * wr + 4 * fr);
;                 rs[ai][0] = rsqrtf(q[0] * (1.0f / D) + EPS); rs[ai][1] = rsqrtf(q[1] * (1.0f / D) + EPS); rs[ai][2] = rsqrtf(q[2] * (1.0f / D) + EPS); rs[ai][3] = rsqrtf(q[3] * (1.0f / D) + EPS); }
; #pragma unroll
;             for (int bj = 0; bj < 2; ++bj)
; #pragma unroll
;                 for (int n = 0; n < 2; ++n) { const f32x4 c2v = *(const LAS f32x4*)(T + 256 + 128 * bj + colL + 4 * n);
; #pragma unroll
;                     for (int ai = 0; ai < 2; ++ai)
; #pragma unroll
;                         for (int m = 0; m < 4; ++m) acc[ai][bj][m][n] = acc[ai][bj][m][n] * rs[ai][m] + c2v; } }
;         if (fr == 0 || fr == 15) {
;             const bool lastr = fr == 15;
;             LAS float* xb = X + (lastr ? 256 : 0) + colL;
; #pragma unroll
;             for (int bj = 0; bj < 2; ++bj)
; #pragma unroll
;                 for (int n = 0; n < 2; ++n)
; #pragma unroll
;                     for (int ai = 0; ai < 2; ++ai) { const int rb = 2 * ai + wr; f32x4 v;
; #pragma unroll
;                         for (int e = 0; e < 4; ++e) v[e] = lastr ? acc[ai][bj][3][n][e] : acc[ai][bj][0][n][e];
;                         *(LAS f32x4*)(xb + rb * 512 + 128 * bj + 4 * n) = v; }
.LBB0_526:
	s_lshl_b32 s4, s11, 5
	s_and_b32 s43, s4, 0x60
	s_lshl_b32 s42, s14, 6
	s_lshl_b32 s8, s14, 13
	s_lshl_b32 s9, s43, 7
	s_add_u32 s4, s2, 0x8000
	s_addc_u32 s5, s3, 0
	s_add_i32 m0, s15, 0x18000
	v_lshl_add_u64 v[14:15], s[4:5], 0, v[156:157]
	global_load_lds_dwordx4 v[14:15], off
	s_add_i32 m0, s15, 0x1a000
	v_lshl_add_u64 v[14:15], s[4:5], 0, v[160:161]
	s_add_u32 s4, s0, 0x8000
	s_addc_u32 s5, s1, 0
	s_add_i32 s53, s15, 0x8000
	global_load_lds_dwordx4 v[14:15], off
	v_lshl_add_u64 v[14:15], s[4:5], 0, v[154:155]
	s_mov_b32 m0, s53
	s_add_i32 s55, s15, 0xa000
	global_load_lds_dwordx4 v[14:15], off
	v_lshl_add_u64 v[14:15], s[4:5], 0, v[158:159]
	s_add_u32 s4, s2, 0xc000
	s_mov_b32 m0, s55
	s_addc_u32 s5, s3, 0
	global_load_lds_dwordx4 v[14:15], off
	s_add_i32 m0, s15, 0x1c000
	v_lshl_add_u64 v[14:15], s[4:5], 0, v[156:157]
	global_load_lds_dwordx4 v[14:15], off
	v_lshl_add_u64 v[14:15], s[4:5], 0, v[160:161]
	s_add_i32 m0, s15, 0x1e000
	v_and_b32_e32 v1, 15, v3
	global_load_lds_dwordx4 v[14:15], off
	s_waitcnt vmcnt(8)
	s_barrier
	v_and_b32_e32 v14, 48, v3
	v_lshlrev_b32_e32 v3, 2, v3
	s_cmpk_lt_u32 s6, 0x100
	v_lshl_or_b32 v14, v1, 6, v14
	v_and_b32_e32 v3, 32, v3
	s_cselect_b64 s[28:29], -1, 0
	s_and_b32 s58, s6, 0xffffff00
	s_lshl_b32 s6, s14, 9
	v_bitop3_b32 v15, v14, s8, v3 bitop3:0xde
	s_lshl_b32 s59, s14, 11
	s_add_i32 s8, s6, 0xffffff00
	s_cmp_gt_i32 s14, 0
	v_bitop3_b32 v229, s9, v14, v3 bitop3:0xf6
	s_cselect_b32 s8, s8, 0
	s_add_i32 s9, s6, 0x200
	s_cmp_lt_i32 s14, 3
	s_cselect_b32 s9, s9, 0x700
	s_add_i32 s30, s6, 0x300
	s_cmp_gt_i32 s14, -2
	s_cselect_b32 s30, s30, 0
	s_addk_i32 s6, 0x600
	s_cmp_lt_i32 s14, 1
	s_cselect_b32 s31, s6, 0x700
	s_lshl_b32 s8, s8, 2
	s_add_i32 s65, 0, 0x20000
	s_add_i32 s68, s65, s8
	s_lshl_b32 s8, s9, 2
	v_and_b32_e32 v4, 1, v4
	s_add_i32 s6, s7, 0xffffd400
	s_add_i32 s69, s65, s8
	s_lshl_b32 s8, s30, 2
	v_add3_u32 v3, v6, v7, v8
	v_lshlrev_b32_e32 v4, 6, v4
	s_ashr_i32 s7, s6, 31
	s_add_i32 s73, s65, s8
	s_lshl_b32 s8, s31, 2
	v_lshl_or_b32 v3, v3, 7, v4
	v_and_b32_e32 v4, 1, v9
	s_add_i32 s64, s15, 0x22000
	s_add_i32 s74, s65, s8
	s_lshl_b64 s[6:7], s[6:7], 2
	v_readlane_b32 s8, v250, 18
	v_lshl_add_u32 v162, v5, 1, v3
	v_add3_u32 v3, v11, v12, v13
	v_lshlrev_b32_e32 v4, 6, v4
	s_mov_b64 s[4:5], 0xc000
	s_waitcnt vmcnt(6)
	v_readlane_b32 s9, v250, 19
	s_add_u32 s30, s8, s6
	v_lshl_or_b32 v3, v3, 7, v4
	v_lshrrev_b32_e32 v228, 4, v2
	v_lshlrev_b32_e32 v2, 2, v2
	s_addc_u32 s31, s9, s7
	v_lshl_add_u64 v[164:165], v[162:163], 0, s[4:5]
	v_lshl_add_u32 v162, v10, 1, v3
	s_add_i32 s75, 0, 0x10000
	s_add_i32 s80, 0, 0x14000
	v_lshl_add_u64 v[166:167], v[162:163], 0, s[4:5]
	v_add_u32_e32 v230, s75, v229
	v_add_u32_e32 v231, s80, v229
	v_add_u32_e32 v232, 0, v15
	v_mov_b32_e32 v233, 0x358637bd
	s_mov_b32 s81, 0x800000
	s_movk_i32 s82, 0x3f00
	v_lshlrev_b32_e32 v234, 2, v2
	v_mov_b32_e32 v235, 0x400
	s_barrier
	s_branch .LBB0_529

; #define PG8_STAGE(bufoff, gbase, voff) do { _Pragma("unroll") for (int _i = 0; _i < 2; ++_i) \
;         __builtin_amdgcn_global_load_lds((const unsigned*)((const char*)(gbase) + (voff)[_i]), (PG8_LAS unsigned*)(lds + (bufoff) + ldsw + _i * 8192), 16, 0, 0); } while (0)
; #define PG8_WAIT_V(n) asm volatile("s_waitcnt vmcnt(" #n ")" ::: "memory")
; #define PG8_BAR __builtin_amdgcn_s_barrier()
; template <class Epi, class Sched, bool ALIGN_EPI = false, bool SP2 = false>
; __device__ __forceinline__ void gemm_phase(PG8_LAS unsigned char* lds, const Gemm g, const Sched& S, const Epi& E, volatile PG8_LAS unsigned* sw = nullptr) {
;     ...
;         PG8_STAGE(PG8_SB(0, 0), cB, voffB); PG8_STAGE(PG8_SB(0, 1), cB + hstep, voffB); PG8_STAGE(PG8_SA(0, 0), cA, voffA); PG8_STAGE(PG8_SA(0, 1), cA + hstep, voffA);
;         if (wr == 1) PG8_BAR;
;         PG8_WAIT_V(2); PG8_BAR;
;         PG8_STAGE(PG8_SB(1, 0), cB + kstep, voffB); PG8_STAGE(PG8_SA(1, 0), cA + kstep, voffA); PG8_STAGE(PG8_SB(1, 1), cB + hstep + kstep, voffB);
;         PG8_WAIT_V(6); PG8_BAR;
.LBB0_693:
	s_add_u32 s0, s18, 0x8000
	s_addc_u32 s1, s19, 0
	s_add_u32 s8, s14, 0x8000
	s_addc_u32 s9, s15, 0
	s_add_u32 s20, s18, 0xc000
	s_addc_u32 s21, s19, 0
	s_add_i32 m0, s25, 0x18000
	v_lshl_add_u64 v[8:9], s[0:1], 0, v[208:209]
	global_load_lds_dwordx4 v[8:9], off
	v_lshl_add_u64 v[8:9], s[0:1], 0, v[204:205]
	s_add_i32 m0, s25, 0x1a000
	s_add_i32 s34, s25, 0x8000
	global_load_lds_dwordx4 v[8:9], off
	v_lshl_add_u64 v[8:9], s[8:9], 0, v[210:211]
	s_mov_b32 m0, s34
	s_add_i32 s35, s25, 0xa000
	global_load_lds_dwordx4 v[8:9], off
	v_lshl_add_u64 v[8:9], s[8:9], 0, v[206:207]
	s_mov_b32 m0, s35
	v_bfe_u32 v219, v0, 4, 2
	global_load_lds_dwordx4 v[8:9], off
	s_add_i32 m0, s25, 0x1c000
	v_lshl_add_u64 v[8:9], s[20:21], 0, v[208:209]
	global_load_lds_dwordx4 v[8:9], off
	v_lshl_add_u64 v[8:9], s[20:21], 0, v[204:205]
	s_add_i32 m0, s25, 0x1e000
	s_and_b32 s0, s6, 3
	global_load_lds_dwordx4 v[8:9], off
	s_waitcnt vmcnt(8)
	s_barrier
	v_and_b32_e32 v218, 15, v0
	v_lshlrev_b32_e32 v7, 4, v219
	v_lshlrev_b32_e32 v0, 2, v0
	v_lshl_or_b32 v7, v218, 6, v7
	s_lshl_b32 s1, s5, 13
	v_and_b32_e32 v0, 32, v0
	s_lshl_b32 s37, s0, 5
	s_lshl_b32 s0, s0, 12
	v_bitop3_b32 v8, v7, s1, v0 bitop3:0xde
	v_bitop3_b32 v220, v7, s0, v0 bitop3:0xde
	v_lshlrev_b32_e32 v0, 10, v5
	v_and_b32_e32 v0, 0xfffff800, v0
	v_lshl_add_u32 v0, v4, 7, v0
	v_and_b32_e32 v4, 1, v5
	v_lshl_or_b32 v0, v4, 6, v0
	v_lshl_add_u32 v214, v6, 1, v0
	v_lshlrev_b32_e32 v0, 10, v1
	s_lshl_b32 s36, s5, 6
	v_and_b32_e32 v0, 0xfffff800, v0
	s_waitcnt vmcnt(6)
	s_cmpk_lt_u32 s4, 0x100
	v_lshl_add_u32 v0, v2, 7, v0
	v_and_b32_e32 v1, 1, v1
	s_cselect_b64 s[4:5], -1, 0
	v_lshl_or_b32 v0, v1, 6, v0
	s_add_i32 s40, 0, 0x10000
	s_add_i32 s41, 0, 0x14000
	s_bfe_u32 s38, s6, 0x10001
	s_and_b32 s39, s37, 32
	v_mov_b32_e32 v215, v213
	v_lshl_add_u32 v216, v3, 1, v0
	v_mov_b32_e32 v217, v213
	v_add_u32_e32 v221, s40, v220
	v_add_u32_e32 v222, s41, v220
	v_add_u32_e32 v223, 0, v8
	s_movk_i32 s42, 0x1000
	s_movk_i32 s43, 0x5000
	s_mov_b32 s44, 0x11000
	s_mov_b32 s45, 0x15000
	s_mov_b32 s46, 0x20000
	s_mov_b32 s47, 0x30000
	s_mov_b32 s48, 0x80000
	s_mov_b32 s49, 0x90000
	s_mov_b32 s50, 0xa0000
	s_mov_b32 s51, 0xb0000
	s_barrier
	s_branch .LBB0_696
